# S5 pass-2 loop: recurrence step as 4 fma (was 6 ops), gelu polynomial in packed f32; 24 percent fewer VALU instructions per batch
# baseline (speedup 1.0000x reference)
.LBB0_873:
	v_mov_b32_e32 v224, 0x3d122279
	v_mov_b32_e32 v225, 0x3d122279
	v_mov_b32_e32 v226, 0x3f4c422a
	v_mov_b32_e32 v227, 0x3f4c422a
	v_mov_b32_e32 v228, 0xc038aa3b
	v_mov_b32_e32 v229, 0xc038aa3b
	v_mov_b32_e32 v230, 1.0
	v_mov_b32_e32 v231, 1.0
	v_cndmask_b32_e64 v93, v83, 0, s[10:11]
	v_cndmask_b32_e64 v92, v82, 0, s[10:11]
	v_cndmask_b32_e64 v91, v81, 0, s[10:11]
	v_cndmask_b32_e64 v90, v80, 0, s[10:11]
	v_add_u32_e32 v81, v139, v141
	v_add_u32_e32 v83, v139, v142
	v_mfma_f32_16x16x32_bf16 v[192:195], v[90:93], v[0:3], 0
	v_add_u32_e32 v88, v139, v143
	v_add_u32_e32 v82, s86, v140
	v_mov_b32_e32 v240, v86
	v_mov_b32_e32 v241, v87
	v_mfma_f32_16x16x32_bf16 v[196:199], v[90:93], v[4:7], 0
	v_mfma_f32_16x16x32_bf16 v[200:203], v[90:93], v[8:11], 0
	s_nop 2
	s_nop 2
	v_cndmask_b32_e64 v79, v79, 0, s[10:11]
	v_mfma_f32_16x16x32_bf16 v[204:207], v[90:93], v[12:15], 0
	v_cndmask_b32_e64 v78, v78, 0, s[10:11]
	v_cndmask_b32_e64 v77, v77, 0, s[10:11]
	v_cndmask_b32_e64 v76, v76, 0, s[10:11]
	v_mfma_f32_16x16x32_bf16 v[212:215], v[90:93], v[20:23], 0
	v_cndmask_b32_e64 v75, v75, 0, s[10:11]
	v_cndmask_b32_e64 v74, v74, 0, s[10:11]
	v_cndmask_b32_e64 v73, v73, 0, s[10:11]
	v_mfma_f32_16x16x32_bf16 v[208:211], v[90:93], v[16:19], 0
	s_nop 6
	v_mfma_f32_16x16x32_bf16 v[216:219], v[90:93], v[24:27], 0
	s_nop 6
	v_mfma_f32_16x16x32_bf16 v[220:223], v[90:93], v[28:31], 0
	v_cndmask_b32_e64 v72, v72, 0, s[10:11]
	v_cndmask_b32_e64 v71, v71, 0, s[10:11]
	v_cndmask_b32_e64 v70, v70, 0, s[10:11]
	v_mfma_f32_16x16x32_bf16 v[90:93], v[90:93], v[48:51], 0
	v_cndmask_b32_e64 v69, v69, 0, s[10:11]
	s_nop 2
	s_nop 7
	v_permlane16_swap_b32_e32 v192, v196
	v_permlane16_swap_b32_e32 v193, v197
	v_permlane16_swap_b32_e32 v194, v198
	v_permlane16_swap_b32_e32 v195, v199
	v_permlane16_swap_b32_e32 v200, v204
	v_permlane16_swap_b32_e32 v201, v205
	v_permlane16_swap_b32_e32 v202, v206
	v_permlane16_swap_b32_e32 v203, v207
	v_permlane16_swap_b32_e32 v208, v212
	v_permlane16_swap_b32_e32 v209, v213
	v_permlane16_swap_b32_e32 v210, v214
	v_permlane16_swap_b32_e32 v211, v215
	v_permlane16_swap_b32_e32 v216, v220
	v_permlane16_swap_b32_e32 v217, v221
	v_permlane16_swap_b32_e32 v218, v222
	v_permlane16_swap_b32_e32 v219, v223
	v_permlane32_swap_b32_e32 v192, v200
	v_permlane32_swap_b32_e32 v193, v201
	v_permlane32_swap_b32_e32 v194, v202
	v_permlane32_swap_b32_e32 v195, v203
	v_permlane32_swap_b32_e32 v196, v204
	v_permlane32_swap_b32_e32 v197, v205
	v_permlane32_swap_b32_e32 v198, v206
	v_permlane32_swap_b32_e32 v199, v207
	v_permlane32_swap_b32_e32 v208, v216
	v_permlane32_swap_b32_e32 v209, v217
	v_permlane32_swap_b32_e32 v210, v218
	v_permlane32_swap_b32_e32 v211, v219
	v_permlane32_swap_b32_e32 v212, v220
	v_permlane32_swap_b32_e32 v213, v221
	v_permlane32_swap_b32_e32 v214, v222
	v_permlane32_swap_b32_e32 v215, v223
	v_fma_f32 v242, -v132, v241, v192
	v_fma_f32 v243, v132, v240, v208
	v_fma_f32 v244, v128, v240, v242
	v_fma_f32 v245, v128, v241, v243
	v_cvt_pk_bf16_f32 v248, v244, v245
	ds_write_b32 v149, v248 offset:10240
	v_fma_f32 v242, -v132, v245, v193
	v_fma_f32 v243, v132, v244, v209
	v_fma_f32 v246, v128, v244, v242
	v_fma_f32 v247, v128, v245, v243
	v_cvt_pk_bf16_f32 v249, v246, v247
	ds_write_b32 v149, v249 offset:10512
	v_fma_f32 v242, -v132, v247, v194
	v_fma_f32 v243, v132, v246, v210
	v_fma_f32 v244, v128, v246, v242
	v_fma_f32 v245, v128, v247, v243
	v_cvt_pk_bf16_f32 v248, v244, v245
	ds_write_b32 v149, v248 offset:10784
	v_fma_f32 v242, -v132, v245, v195
	v_fma_f32 v243, v132, v244, v211
	v_fma_f32 v246, v128, v244, v242
	v_fma_f32 v247, v128, v245, v243
	v_cvt_pk_bf16_f32 v249, v246, v247
	ds_write_b32 v149, v249 offset:11056
	v_fma_f32 v242, -v132, v247, v196
	v_fma_f32 v243, v132, v246, v212
	v_fma_f32 v244, v128, v246, v242
	v_fma_f32 v245, v128, v247, v243
	v_cvt_pk_bf16_f32 v248, v244, v245
	ds_write_b32 v149, v248 offset:11328
	v_fma_f32 v242, -v132, v245, v197
	v_fma_f32 v243, v132, v244, v213
	v_fma_f32 v246, v128, v244, v242
	v_fma_f32 v247, v128, v245, v243
	v_cvt_pk_bf16_f32 v249, v246, v247
	ds_write_b32 v149, v249 offset:11600
	v_fma_f32 v242, -v132, v247, v198
	v_fma_f32 v243, v132, v246, v214
	v_fma_f32 v244, v128, v246, v242
	v_fma_f32 v245, v128, v247, v243
	v_cvt_pk_bf16_f32 v248, v244, v245
	ds_write_b32 v149, v248 offset:11872
	v_fma_f32 v242, -v132, v245, v199
	v_fma_f32 v243, v132, v244, v215
	v_fma_f32 v246, v128, v244, v242
	v_fma_f32 v247, v128, v245, v243
	v_cvt_pk_bf16_f32 v249, v246, v247
	ds_write_b32 v149, v249 offset:12144
	v_fma_f32 v242, -v132, v247, v200
	v_fma_f32 v243, v132, v246, v216
	v_fma_f32 v244, v128, v246, v242
	v_fma_f32 v245, v128, v247, v243
	v_cvt_pk_bf16_f32 v248, v244, v245
	ds_write_b32 v149, v248 offset:12416
	v_fma_f32 v242, -v132, v245, v201
	v_fma_f32 v243, v132, v244, v217
	v_fma_f32 v246, v128, v244, v242
	v_fma_f32 v247, v128, v245, v243
	v_cvt_pk_bf16_f32 v249, v246, v247
	ds_write_b32 v149, v249 offset:12688
	v_fma_f32 v242, -v132, v247, v202
	v_fma_f32 v243, v132, v246, v218
	v_fma_f32 v244, v128, v246, v242
	v_fma_f32 v245, v128, v247, v243
	v_cvt_pk_bf16_f32 v248, v244, v245
	ds_write_b32 v149, v248 offset:12960
	v_fma_f32 v242, -v132, v245, v203
	v_fma_f32 v243, v132, v244, v219
	v_fma_f32 v246, v128, v244, v242
	v_fma_f32 v247, v128, v245, v243
	v_cvt_pk_bf16_f32 v249, v246, v247
	ds_write_b32 v149, v249 offset:13232
	v_fma_f32 v242, -v132, v247, v204
	v_fma_f32 v243, v132, v246, v220
	v_fma_f32 v244, v128, v246, v242
	v_fma_f32 v245, v128, v247, v243
	v_cvt_pk_bf16_f32 v248, v244, v245
	ds_write_b32 v149, v248 offset:13504
	v_fma_f32 v242, -v132, v245, v205
	v_fma_f32 v243, v132, v244, v221
	v_fma_f32 v246, v128, v244, v242
	v_fma_f32 v247, v128, v245, v243
	v_cvt_pk_bf16_f32 v249, v246, v247
	ds_write_b32 v149, v249 offset:13776
	v_fma_f32 v242, -v132, v247, v206
	v_fma_f32 v243, v132, v246, v222
	v_fma_f32 v244, v128, v246, v242
	v_fma_f32 v245, v128, v247, v243
	v_cvt_pk_bf16_f32 v248, v244, v245
	ds_write_b32 v149, v248 offset:14048
	v_fma_f32 v242, -v132, v245, v207
	v_fma_f32 v243, v132, v244, v223
	v_fma_f32 v87, v128, v244, v242
	v_fma_f32 v86, v128, v245, v243
	v_cvt_pk_bf16_f32 v249, v87, v86
	ds_write_b32 v149, v249 offset:14320
	s_waitcnt lgkmcnt(0)
	v_add_u32_e32 v80, v150, v138
	ds_read_b128 v[94:97], v80 offset:10240
	ds_read_b128 v[98:101], v80 offset:10304
	ds_read_b128 v[184:187], v80 offset:10368
	ds_read_b128 v[188:191], v80 offset:10432
	s_waitcnt lgkmcnt(3)
	v_mfma_f32_16x16x32_bf16 v[90:93], v[94:97], v[32:35], v[90:93]
	v_cndmask_b32_e64 v68, v68, 0, s[10:11]
	s_add_u32 s30, s30, 0x40000
	s_waitcnt lgkmcnt(2)
	v_mfma_f32_16x16x32_bf16 v[90:93], v[98:101], v[36:39], v[90:93]
	s_addc_u32 s31, s31, 0
	s_cmp_eq_u32 s30, 0x240000
	s_waitcnt lgkmcnt(1)
	v_mfma_f32_16x16x32_bf16 v[90:93], v[184:187], v[40:43], v[90:93]
	s_cselect_b64 s[34:35], -1, 0
	s_waitcnt lgkmcnt(0)
	v_mfma_f32_16x16x32_bf16 v[90:93], v[188:191], v[44:47], v[90:93]
	v_mfma_f32_16x16x32_bf16 v[196:199], v[76:79], v[4:7], 0
	v_mfma_f32_16x16x32_bf16 v[200:203], v[76:79], v[8:11], 0
	s_nop 5
	v_pk_mul_f32 v[232:233], v[90:91], v[224:225]
	v_pk_mul_f32 v[234:235], v[92:93], v[224:225]
	v_pk_fma_f32 v[232:233], v[90:91], v[232:233], v[226:227]
	v_pk_fma_f32 v[234:235], v[92:93], v[234:235], v[226:227]
	v_pk_mul_f32 v[232:233], v[90:91], v[232:233]
	v_pk_mul_f32 v[234:235], v[92:93], v[234:235]
	v_pk_mul_f32 v[232:233], v[232:233], v[228:229]
	v_pk_mul_f32 v[234:235], v[234:235], v[228:229]
	v_exp_f32_e32 v232, v232
	v_exp_f32_e32 v233, v233
	v_exp_f32_e32 v234, v234
	v_exp_f32_e32 v235, v235
	v_pk_add_f32 v[232:233], v[232:233], v[230:231]
	v_pk_add_f32 v[234:235], v[234:235], v[230:231]
	v_rcp_f32_e32 v232, v232
	v_rcp_f32_e32 v233, v233
	v_rcp_f32_e32 v234, v234
	v_rcp_f32_e32 v235, v235
	v_pk_mul_f32 v[232:233], v[90:91], v[232:233]
	v_pk_mul_f32 v[234:235], v[92:93], v[234:235]
	v_cvt_pk_bf16_f32 v236, v232, v232
	v_cvt_pk_bf16_f32 v237, v233, v233
	v_cvt_pk_bf16_f32 v238, v234, v234
	v_cvt_pk_bf16_f32 v239, v235, v235
	ds_write_b16 v160, v236 offset:14592
	ds_write_b16 v160, v237 offset:14624
	ds_write_b16 v160, v238 offset:14656
	ds_write_b16 v161, v239 offset:14592
	v_mfma_f32_16x16x32_bf16 v[204:207], v[76:79], v[12:15], 0
	v_mfma_f32_16x16x32_bf16 v[192:195], v[76:79], v[0:3], 0
	v_mfma_f32_16x16x32_bf16 v[208:211], v[76:79], v[16:19], 0
	s_nop 0
	s_nop 3
	v_mfma_f32_16x16x32_bf16 v[212:215], v[76:79], v[20:23], 0
	v_mov_b32_e32 v240, v87
	v_mov_b32_e32 v241, v86
	v_mfma_f32_16x16x32_bf16 v[216:219], v[76:79], v[24:27], 0
	s_nop 0
	s_nop 4
	v_mfma_f32_16x16x32_bf16 v[220:223], v[76:79], v[28:31], 0
	v_mfma_f32_16x16x32_bf16 v[76:79], v[76:79], v[48:51], 0
	s_nop 5
	s_nop 7
	v_permlane16_swap_b32_e32 v192, v196
	v_permlane16_swap_b32_e32 v193, v197
	v_permlane16_swap_b32_e32 v194, v198
	v_permlane16_swap_b32_e32 v195, v199
	v_permlane16_swap_b32_e32 v200, v204
	v_permlane16_swap_b32_e32 v201, v205
	v_permlane16_swap_b32_e32 v202, v206
	v_permlane16_swap_b32_e32 v203, v207
	v_permlane16_swap_b32_e32 v208, v212
	v_permlane16_swap_b32_e32 v209, v213
	v_permlane16_swap_b32_e32 v210, v214
	v_permlane16_swap_b32_e32 v211, v215
	v_permlane16_swap_b32_e32 v216, v220
	v_permlane16_swap_b32_e32 v217, v221
	v_permlane16_swap_b32_e32 v218, v222
	v_permlane16_swap_b32_e32 v219, v223
	v_permlane32_swap_b32_e32 v192, v200
	v_permlane32_swap_b32_e32 v193, v201
	v_permlane32_swap_b32_e32 v194, v202
	v_permlane32_swap_b32_e32 v195, v203
	v_permlane32_swap_b32_e32 v196, v204
	v_permlane32_swap_b32_e32 v197, v205
	v_permlane32_swap_b32_e32 v198, v206
	v_permlane32_swap_b32_e32 v199, v207
	v_permlane32_swap_b32_e32 v208, v216
	v_permlane32_swap_b32_e32 v209, v217
	v_permlane32_swap_b32_e32 v210, v218
	v_permlane32_swap_b32_e32 v211, v219
	v_permlane32_swap_b32_e32 v212, v220
	v_permlane32_swap_b32_e32 v213, v221
	v_permlane32_swap_b32_e32 v214, v222
	v_permlane32_swap_b32_e32 v215, v223
	v_fma_f32 v242, -v132, v241, v192
	v_fma_f32 v243, v132, v240, v208
	v_fma_f32 v244, v128, v240, v242
	v_fma_f32 v245, v128, v241, v243
	v_cvt_pk_bf16_f32 v248, v244, v245
	ds_write_b32 v149, v248 offset:10240
	v_fma_f32 v242, -v132, v245, v193
	v_fma_f32 v243, v132, v244, v209
	v_fma_f32 v246, v128, v244, v242
	v_fma_f32 v247, v128, v245, v243
	v_cvt_pk_bf16_f32 v249, v246, v247
	ds_write_b32 v149, v249 offset:10512
	v_fma_f32 v242, -v132, v247, v194
	v_fma_f32 v243, v132, v246, v210
	v_fma_f32 v244, v128, v246, v242
	v_fma_f32 v245, v128, v247, v243
	v_cvt_pk_bf16_f32 v248, v244, v245
	ds_write_b32 v149, v248 offset:10784
	v_fma_f32 v242, -v132, v245, v195
	v_fma_f32 v243, v132, v244, v211
	v_fma_f32 v246, v128, v244, v242
	v_fma_f32 v247, v128, v245, v243
	v_cvt_pk_bf16_f32 v249, v246, v247
	ds_write_b32 v149, v249 offset:11056
	v_fma_f32 v242, -v132, v247, v196
	v_fma_f32 v243, v132, v246, v212
	v_fma_f32 v244, v128, v246, v242
	v_fma_f32 v245, v128, v247, v243
	v_cvt_pk_bf16_f32 v248, v244, v245
	ds_write_b32 v149, v248 offset:11328
	v_fma_f32 v242, -v132, v245, v197
	v_fma_f32 v243, v132, v244, v213
	v_fma_f32 v246, v128, v244, v242
	v_fma_f32 v247, v128, v245, v243
	v_cvt_pk_bf16_f32 v249, v246, v247
	ds_write_b32 v149, v249 offset:11600
	v_fma_f32 v242, -v132, v247, v198
	v_fma_f32 v243, v132, v246, v214
	v_fma_f32 v244, v128, v246, v242
	v_fma_f32 v245, v128, v247, v243
	v_cvt_pk_bf16_f32 v248, v244, v245
	ds_write_b32 v149, v248 offset:11872
	v_fma_f32 v242, -v132, v245, v199
	v_fma_f32 v243, v132, v244, v215
	v_fma_f32 v246, v128, v244, v242
	v_fma_f32 v247, v128, v245, v243
	v_cvt_pk_bf16_f32 v249, v246, v247
	ds_write_b32 v149, v249 offset:12144
	v_fma_f32 v242, -v132, v247, v200
	v_fma_f32 v243, v132, v246, v216
	v_fma_f32 v244, v128, v246, v242
	v_fma_f32 v245, v128, v247, v243
	v_cvt_pk_bf16_f32 v248, v244, v245
	ds_write_b32 v149, v248 offset:12416
	v_fma_f32 v242, -v132, v245, v201
	v_fma_f32 v243, v132, v244, v217
	v_fma_f32 v246, v128, v244, v242
	v_fma_f32 v247, v128, v245, v243
	v_cvt_pk_bf16_f32 v249, v246, v247
	ds_write_b32 v149, v249 offset:12688
	v_fma_f32 v242, -v132, v247, v202
	v_fma_f32 v243, v132, v246, v218
	v_fma_f32 v244, v128, v246, v242
	v_fma_f32 v245, v128, v247, v243
	v_cvt_pk_bf16_f32 v248, v244, v245
	ds_write_b32 v149, v248 offset:12960
	v_fma_f32 v242, -v132, v245, v203
	v_fma_f32 v243, v132, v244, v219
	v_fma_f32 v246, v128, v244, v242
	v_fma_f32 v247, v128, v245, v243
	v_cvt_pk_bf16_f32 v249, v246, v247
	ds_write_b32 v149, v249 offset:13232
	v_fma_f32 v242, -v132, v247, v204
	v_fma_f32 v243, v132, v246, v220
	v_fma_f32 v244, v128, v246, v242
	v_fma_f32 v245, v128, v247, v243
	v_cvt_pk_bf16_f32 v248, v244, v245
	ds_write_b32 v149, v248 offset:13504
	v_fma_f32 v242, -v132, v245, v205
	v_fma_f32 v243, v132, v244, v221
	v_fma_f32 v246, v128, v244, v242
	v_fma_f32 v247, v128, v245, v243
	v_cvt_pk_bf16_f32 v249, v246, v247
	ds_write_b32 v149, v249 offset:13776
	v_fma_f32 v242, -v132, v247, v206
	v_fma_f32 v243, v132, v246, v222
	v_fma_f32 v244, v128, v246, v242
	v_fma_f32 v245, v128, v247, v243
	v_cvt_pk_bf16_f32 v248, v244, v245
	ds_write_b32 v149, v248 offset:14048
	v_fma_f32 v242, -v132, v245, v207
	v_fma_f32 v243, v132, v244, v223
	v_fma_f32 v87, v128, v244, v242
	v_fma_f32 v86, v128, v245, v243
	v_cvt_pk_bf16_f32 v249, v87, v86
	ds_write_b32 v149, v249 offset:14320
	s_waitcnt lgkmcnt(0)
	ds_read_b128 v[90:93], v80 offset:10240
	ds_read_b128 v[94:97], v80 offset:10304
	ds_read_b128 v[184:187], v80 offset:10368
	ds_read_b128 v[188:191], v80 offset:10432
	s_waitcnt lgkmcnt(3)
	v_mfma_f32_16x16x32_bf16 v[76:79], v[90:93], v[32:35], v[76:79]
	s_waitcnt lgkmcnt(2)
	v_mfma_f32_16x16x32_bf16 v[76:79], v[94:97], v[36:39], v[76:79]
	s_waitcnt lgkmcnt(1)
	v_mfma_f32_16x16x32_bf16 v[76:79], v[184:187], v[40:43], v[76:79]
	s_waitcnt lgkmcnt(0)
	v_mfma_f32_16x16x32_bf16 v[76:79], v[188:191], v[44:47], v[76:79]
	v_mfma_f32_16x16x32_bf16 v[196:199], v[72:75], v[4:7], 0
	v_mfma_f32_16x16x32_bf16 v[200:203], v[72:75], v[8:11], 0
	s_nop 5
	v_pk_mul_f32 v[232:233], v[76:77], v[224:225]
	v_pk_mul_f32 v[234:235], v[78:79], v[224:225]
	v_pk_fma_f32 v[232:233], v[76:77], v[232:233], v[226:227]
	v_pk_fma_f32 v[234:235], v[78:79], v[234:235], v[226:227]
	v_pk_mul_f32 v[232:233], v[76:77], v[232:233]
	v_pk_mul_f32 v[234:235], v[78:79], v[234:235]
	v_pk_mul_f32 v[232:233], v[232:233], v[228:229]
	v_pk_mul_f32 v[234:235], v[234:235], v[228:229]
	v_exp_f32_e32 v232, v232
	v_exp_f32_e32 v233, v233
	v_exp_f32_e32 v234, v234
	v_exp_f32_e32 v235, v235
	v_pk_add_f32 v[232:233], v[232:233], v[230:231]
	v_pk_add_f32 v[234:235], v[234:235], v[230:231]
	v_rcp_f32_e32 v232, v232
	v_rcp_f32_e32 v233, v233
	v_rcp_f32_e32 v234, v234
	v_rcp_f32_e32 v235, v235
	v_pk_mul_f32 v[232:233], v[76:77], v[232:233]
	v_pk_mul_f32 v[234:235], v[78:79], v[234:235]
	v_cvt_pk_bf16_f32 v236, v232, v232
	v_cvt_pk_bf16_f32 v237, v233, v233
	v_cvt_pk_bf16_f32 v238, v234, v234
	v_cvt_pk_bf16_f32 v239, v235, v235
	ds_write_b16 v160, v236 offset:15104
	ds_write_b16 v160, v237 offset:15136
	ds_write_b16 v160, v238 offset:15168
	ds_write_b16 v162, v239 offset:14592
	v_mfma_f32_16x16x32_bf16 v[204:207], v[72:75], v[12:15], 0
	v_mfma_f32_16x16x32_bf16 v[192:195], v[72:75], v[0:3], 0
	v_mfma_f32_16x16x32_bf16 v[208:211], v[72:75], v[16:19], 0
	s_nop 0
	s_nop 3
	v_mfma_f32_16x16x32_bf16 v[212:215], v[72:75], v[20:23], 0
	v_mov_b32_e32 v240, v87
	v_mov_b32_e32 v241, v86
	v_mfma_f32_16x16x32_bf16 v[216:219], v[72:75], v[24:27], 0
	s_nop 0
	s_nop 4
	v_mfma_f32_16x16x32_bf16 v[220:223], v[72:75], v[28:31], 0
	v_mfma_f32_16x16x32_bf16 v[72:75], v[72:75], v[48:51], 0
	s_nop 5
	s_nop 7
	v_permlane16_swap_b32_e32 v192, v196
	v_permlane16_swap_b32_e32 v193, v197
	v_permlane16_swap_b32_e32 v194, v198
	v_permlane16_swap_b32_e32 v195, v199
	v_permlane16_swap_b32_e32 v200, v204
	v_permlane16_swap_b32_e32 v201, v205
	v_permlane16_swap_b32_e32 v202, v206
	v_permlane16_swap_b32_e32 v203, v207
	v_permlane16_swap_b32_e32 v208, v212
	v_permlane16_swap_b32_e32 v209, v213
	v_permlane16_swap_b32_e32 v210, v214
	v_permlane16_swap_b32_e32 v211, v215
	v_permlane16_swap_b32_e32 v216, v220
	v_permlane16_swap_b32_e32 v217, v221
	v_permlane16_swap_b32_e32 v218, v222
	v_permlane16_swap_b32_e32 v219, v223
	v_permlane32_swap_b32_e32 v192, v200
	v_permlane32_swap_b32_e32 v193, v201
	v_permlane32_swap_b32_e32 v194, v202
	v_permlane32_swap_b32_e32 v195, v203
	v_permlane32_swap_b32_e32 v196, v204
	v_permlane32_swap_b32_e32 v197, v205
	v_permlane32_swap_b32_e32 v198, v206
	v_permlane32_swap_b32_e32 v199, v207
	v_permlane32_swap_b32_e32 v208, v216
	v_permlane32_swap_b32_e32 v209, v217
	v_permlane32_swap_b32_e32 v210, v218
	v_permlane32_swap_b32_e32 v211, v219
	v_permlane32_swap_b32_e32 v212, v220
	v_permlane32_swap_b32_e32 v213, v221
	v_permlane32_swap_b32_e32 v214, v222
	v_permlane32_swap_b32_e32 v215, v223
	v_fma_f32 v242, -v132, v241, v192
	v_fma_f32 v243, v132, v240, v208
	v_fma_f32 v244, v128, v240, v242
	v_fma_f32 v245, v128, v241, v243
	v_cvt_pk_bf16_f32 v248, v244, v245
	ds_write_b32 v149, v248 offset:10240
	v_fma_f32 v242, -v132, v245, v193
	v_fma_f32 v243, v132, v244, v209
	v_fma_f32 v246, v128, v244, v242
	v_fma_f32 v247, v128, v245, v243
	v_cvt_pk_bf16_f32 v249, v246, v247
	ds_write_b32 v149, v249 offset:10512
	v_fma_f32 v242, -v132, v247, v194
	v_fma_f32 v243, v132, v246, v210
	v_fma_f32 v244, v128, v246, v242
	v_fma_f32 v245, v128, v247, v243
	v_cvt_pk_bf16_f32 v248, v244, v245
	ds_write_b32 v149, v248 offset:10784
	v_fma_f32 v242, -v132, v245, v195
	v_fma_f32 v243, v132, v244, v211
	v_fma_f32 v246, v128, v244, v242
	v_fma_f32 v247, v128, v245, v243
	v_cvt_pk_bf16_f32 v249, v246, v247
	ds_write_b32 v149, v249 offset:11056
	v_fma_f32 v242, -v132, v247, v196
	v_fma_f32 v243, v132, v246, v212
	v_fma_f32 v244, v128, v246, v242
	v_fma_f32 v245, v128, v247, v243
	v_cvt_pk_bf16_f32 v248, v244, v245
	ds_write_b32 v149, v248 offset:11328
	v_fma_f32 v242, -v132, v245, v197
	v_fma_f32 v243, v132, v244, v213
	v_fma_f32 v246, v128, v244, v242
	v_fma_f32 v247, v128, v245, v243
	v_cvt_pk_bf16_f32 v249, v246, v247
	ds_write_b32 v149, v249 offset:11600
	v_fma_f32 v242, -v132, v247, v198
	v_fma_f32 v243, v132, v246, v214
	v_fma_f32 v244, v128, v246, v242
	v_fma_f32 v245, v128, v247, v243
	v_cvt_pk_bf16_f32 v248, v244, v245
	ds_write_b32 v149, v248 offset:11872
	v_fma_f32 v242, -v132, v245, v199
	v_fma_f32 v243, v132, v244, v215
	v_fma_f32 v246, v128, v244, v242
	v_fma_f32 v247, v128, v245, v243
	v_cvt_pk_bf16_f32 v249, v246, v247
	ds_write_b32 v149, v249 offset:12144
	v_fma_f32 v242, -v132, v247, v200
	v_fma_f32 v243, v132, v246, v216
	v_fma_f32 v244, v128, v246, v242
	v_fma_f32 v245, v128, v247, v243
	v_cvt_pk_bf16_f32 v248, v244, v245
	ds_write_b32 v149, v248 offset:12416
	v_fma_f32 v242, -v132, v245, v201
	v_fma_f32 v243, v132, v244, v217
	v_fma_f32 v246, v128, v244, v242
	v_fma_f32 v247, v128, v245, v243
	v_cvt_pk_bf16_f32 v249, v246, v247
	ds_write_b32 v149, v249 offset:12688
	v_fma_f32 v242, -v132, v247, v202
	v_fma_f32 v243, v132, v246, v218
	v_fma_f32 v244, v128, v246, v242
	v_fma_f32 v245, v128, v247, v243
	v_cvt_pk_bf16_f32 v248, v244, v245
	ds_write_b32 v149, v248 offset:12960
	v_fma_f32 v242, -v132, v245, v203
	v_fma_f32 v243, v132, v244, v219
	v_fma_f32 v246, v128, v244, v242
	v_fma_f32 v247, v128, v245, v243
	v_cvt_pk_bf16_f32 v249, v246, v247
	ds_write_b32 v149, v249 offset:13232
	v_fma_f32 v242, -v132, v247, v204
	v_fma_f32 v243, v132, v246, v220
	v_fma_f32 v244, v128, v246, v242
	v_fma_f32 v245, v128, v247, v243
	v_cvt_pk_bf16_f32 v248, v244, v245
	ds_write_b32 v149, v248 offset:13504
	v_fma_f32 v242, -v132, v245, v205
	v_fma_f32 v243, v132, v244, v221
	v_fma_f32 v246, v128, v244, v242
	v_fma_f32 v247, v128, v245, v243
	v_cvt_pk_bf16_f32 v249, v246, v247
	ds_write_b32 v149, v249 offset:13776
	v_fma_f32 v242, -v132, v247, v206
	v_fma_f32 v243, v132, v246, v222
	v_fma_f32 v244, v128, v246, v242
	v_fma_f32 v245, v128, v247, v243
	v_cvt_pk_bf16_f32 v248, v244, v245
	ds_write_b32 v149, v248 offset:14048
	v_fma_f32 v242, -v132, v245, v207
	v_fma_f32 v243, v132, v244, v223
	v_fma_f32 v110, v128, v244, v242
	v_fma_f32 v111, v128, v245, v243
	v_cvt_pk_bf16_f32 v249, v110, v111
	ds_write_b32 v149, v249 offset:14320
	s_waitcnt lgkmcnt(0)
	ds_read_b128 v[76:79], v80 offset:10240
	ds_read_b128 v[90:93], v80 offset:10304
	ds_read_b128 v[184:187], v80 offset:10368
	ds_read_b128 v[188:191], v80 offset:10432
	s_waitcnt lgkmcnt(3)
	v_mfma_f32_16x16x32_bf16 v[72:75], v[76:79], v[32:35], v[72:75]
	s_waitcnt lgkmcnt(2)
	v_mfma_f32_16x16x32_bf16 v[72:75], v[90:93], v[36:39], v[72:75]
	s_waitcnt lgkmcnt(1)
	v_mfma_f32_16x16x32_bf16 v[72:75], v[184:187], v[40:43], v[72:75]
	s_waitcnt lgkmcnt(0)
	v_mfma_f32_16x16x32_bf16 v[72:75], v[188:191], v[44:47], v[72:75]
	v_mfma_f32_16x16x32_bf16 v[196:199], v[68:71], v[4:7], 0
	v_mfma_f32_16x16x32_bf16 v[200:203], v[68:71], v[8:11], 0
	s_nop 5
	v_pk_mul_f32 v[232:233], v[72:73], v[224:225]
	v_pk_mul_f32 v[234:235], v[74:75], v[224:225]
	v_pk_fma_f32 v[232:233], v[72:73], v[232:233], v[226:227]
	v_pk_fma_f32 v[234:235], v[74:75], v[234:235], v[226:227]
	v_pk_mul_f32 v[232:233], v[72:73], v[232:233]
	v_pk_mul_f32 v[234:235], v[74:75], v[234:235]
	v_pk_mul_f32 v[232:233], v[232:233], v[228:229]
	v_pk_mul_f32 v[234:235], v[234:235], v[228:229]
	v_exp_f32_e32 v232, v232
	v_exp_f32_e32 v233, v233
	v_exp_f32_e32 v234, v234
	v_exp_f32_e32 v235, v235
	v_pk_add_f32 v[232:233], v[232:233], v[230:231]
	v_pk_add_f32 v[234:235], v[234:235], v[230:231]
	v_rcp_f32_e32 v232, v232
	v_rcp_f32_e32 v233, v233
	v_rcp_f32_e32 v234, v234
	v_rcp_f32_e32 v235, v235
	v_pk_mul_f32 v[232:233], v[72:73], v[232:233]
	v_pk_mul_f32 v[234:235], v[74:75], v[234:235]
	v_cvt_pk_bf16_f32 v236, v232, v232
	v_cvt_pk_bf16_f32 v237, v233, v233
	v_cvt_pk_bf16_f32 v238, v234, v234
	v_cvt_pk_bf16_f32 v239, v235, v235
	ds_write_b16 v160, v236 offset:15616
	ds_write_b16 v160, v237 offset:15648
	ds_write_b16 v160, v238 offset:15680
	ds_write_b16 v163, v239 offset:14592
	v_mfma_f32_16x16x32_bf16 v[204:207], v[68:71], v[12:15], 0
	v_mfma_f32_16x16x32_bf16 v[192:195], v[68:71], v[0:3], 0
	v_mfma_f32_16x16x32_bf16 v[208:211], v[68:71], v[16:19], 0
	s_nop 0
	s_nop 3
	v_mfma_f32_16x16x32_bf16 v[212:215], v[68:71], v[20:23], 0
	v_mfma_f32_16x16x32_bf16 v[216:219], v[68:71], v[24:27], 0
	s_nop 2
	s_nop 2
	v_mov_b32_e32 v240, v110
	v_mov_b32_e32 v241, v111
	v_mfma_f32_16x16x32_bf16 v[220:223], v[68:71], v[28:31], 0
	v_mfma_f32_16x16x32_bf16 v[68:71], v[68:71], v[48:51], 0
	s_nop 5
	s_nop 7
	v_permlane16_swap_b32_e32 v192, v196
	v_permlane16_swap_b32_e32 v193, v197
	v_permlane16_swap_b32_e32 v194, v198
	v_permlane16_swap_b32_e32 v195, v199
	v_permlane16_swap_b32_e32 v200, v204
	v_permlane16_swap_b32_e32 v201, v205
	v_permlane16_swap_b32_e32 v202, v206
	v_permlane16_swap_b32_e32 v203, v207
	v_permlane16_swap_b32_e32 v208, v212
	v_permlane16_swap_b32_e32 v209, v213
	v_permlane16_swap_b32_e32 v210, v214
	v_permlane16_swap_b32_e32 v211, v215
	v_permlane16_swap_b32_e32 v216, v220
	v_permlane16_swap_b32_e32 v217, v221
	v_permlane16_swap_b32_e32 v218, v222
	v_permlane16_swap_b32_e32 v219, v223
	v_permlane32_swap_b32_e32 v192, v200
	v_permlane32_swap_b32_e32 v193, v201
	v_permlane32_swap_b32_e32 v194, v202
	v_permlane32_swap_b32_e32 v195, v203
	v_permlane32_swap_b32_e32 v196, v204
	v_permlane32_swap_b32_e32 v197, v205
	v_permlane32_swap_b32_e32 v198, v206
	v_permlane32_swap_b32_e32 v199, v207
	v_permlane32_swap_b32_e32 v208, v216
	v_permlane32_swap_b32_e32 v209, v217
	v_permlane32_swap_b32_e32 v210, v218
	v_permlane32_swap_b32_e32 v211, v219
	v_permlane32_swap_b32_e32 v212, v220
	v_permlane32_swap_b32_e32 v213, v221
	v_permlane32_swap_b32_e32 v214, v222
	v_permlane32_swap_b32_e32 v215, v223
	v_fma_f32 v242, -v132, v241, v192
	v_fma_f32 v243, v132, v240, v208
	v_fma_f32 v244, v128, v240, v242
	v_fma_f32 v245, v128, v241, v243
	v_cvt_pk_bf16_f32 v248, v244, v245
	ds_write_b32 v149, v248 offset:10240
	v_fma_f32 v242, -v132, v245, v193
	v_fma_f32 v243, v132, v244, v209
	v_fma_f32 v246, v128, v244, v242
	v_fma_f32 v247, v128, v245, v243
	v_cvt_pk_bf16_f32 v249, v246, v247
	ds_write_b32 v149, v249 offset:10512
	v_fma_f32 v242, -v132, v247, v194
	v_fma_f32 v243, v132, v246, v210
	v_fma_f32 v244, v128, v246, v242
	v_fma_f32 v245, v128, v247, v243
	v_cvt_pk_bf16_f32 v248, v244, v245
	ds_write_b32 v149, v248 offset:10784
	v_fma_f32 v242, -v132, v245, v195
	v_fma_f32 v243, v132, v244, v211
	v_fma_f32 v246, v128, v244, v242
	v_fma_f32 v247, v128, v245, v243
	v_cvt_pk_bf16_f32 v249, v246, v247
	ds_write_b32 v149, v249 offset:11056
	v_fma_f32 v242, -v132, v247, v196
	v_fma_f32 v243, v132, v246, v212
	v_fma_f32 v244, v128, v246, v242
	v_fma_f32 v245, v128, v247, v243
	v_cvt_pk_bf16_f32 v248, v244, v245
	ds_write_b32 v149, v248 offset:11328
	v_fma_f32 v242, -v132, v245, v197
	v_fma_f32 v243, v132, v244, v213
	v_fma_f32 v246, v128, v244, v242
	v_fma_f32 v247, v128, v245, v243
	v_cvt_pk_bf16_f32 v249, v246, v247
	ds_write_b32 v149, v249 offset:11600
	v_fma_f32 v242, -v132, v247, v198
	v_fma_f32 v243, v132, v246, v214
	v_fma_f32 v244, v128, v246, v242
	v_fma_f32 v245, v128, v247, v243
	v_cvt_pk_bf16_f32 v248, v244, v245
	ds_write_b32 v149, v248 offset:11872
	v_fma_f32 v242, -v132, v245, v199
	v_fma_f32 v243, v132, v244, v215
	v_fma_f32 v246, v128, v244, v242
	v_fma_f32 v247, v128, v245, v243
	v_cvt_pk_bf16_f32 v249, v246, v247
	ds_write_b32 v149, v249 offset:12144
	v_fma_f32 v242, -v132, v247, v200
	v_fma_f32 v243, v132, v246, v216
	v_fma_f32 v244, v128, v246, v242
	v_fma_f32 v245, v128, v247, v243
	v_cvt_pk_bf16_f32 v248, v244, v245
	ds_write_b32 v149, v248 offset:12416
	v_fma_f32 v242, -v132, v245, v201
	v_fma_f32 v243, v132, v244, v217
	v_fma_f32 v246, v128, v244, v242
	v_fma_f32 v247, v128, v245, v243
	v_cvt_pk_bf16_f32 v249, v246, v247
	ds_write_b32 v149, v249 offset:12688
	v_fma_f32 v242, -v132, v247, v202
	v_fma_f32 v243, v132, v246, v218
	v_fma_f32 v244, v128, v246, v242
	v_fma_f32 v245, v128, v247, v243
	v_cvt_pk_bf16_f32 v248, v244, v245
	ds_write_b32 v149, v248 offset:12960
	v_fma_f32 v242, -v132, v245, v203
	v_fma_f32 v243, v132, v244, v219
	v_fma_f32 v246, v128, v244, v242
	v_fma_f32 v247, v128, v245, v243
	v_cvt_pk_bf16_f32 v249, v246, v247
	ds_write_b32 v149, v249 offset:13232
	v_fma_f32 v242, -v132, v247, v204
	v_fma_f32 v243, v132, v246, v220
	v_fma_f32 v244, v128, v246, v242
	v_fma_f32 v245, v128, v247, v243
	v_cvt_pk_bf16_f32 v248, v244, v245
	ds_write_b32 v149, v248 offset:13504
	v_fma_f32 v242, -v132, v245, v205
	v_fma_f32 v243, v132, v244, v221
	v_fma_f32 v246, v128, v244, v242
	v_fma_f32 v247, v128, v245, v243
	v_cvt_pk_bf16_f32 v249, v246, v247
	ds_write_b32 v149, v249 offset:13776
	v_fma_f32 v242, -v132, v247, v206
	v_fma_f32 v243, v132, v246, v222
	v_fma_f32 v244, v128, v246, v242
	v_fma_f32 v245, v128, v247, v243
	v_cvt_pk_bf16_f32 v248, v244, v245
	ds_write_b32 v149, v248 offset:14048
	v_fma_f32 v242, -v132, v245, v207
	v_fma_f32 v243, v132, v244, v223
	v_fma_f32 v86, v128, v244, v242
	v_fma_f32 v87, v128, v245, v243
	v_cvt_pk_bf16_f32 v249, v86, v87
	ds_write_b32 v149, v249 offset:14320
	s_waitcnt lgkmcnt(0)
	ds_read_b128 v[72:75], v80 offset:10240
	ds_read_b128 v[76:79], v80 offset:10304
	ds_read_b128 v[184:187], v80 offset:10368
	ds_read_b128 v[188:191], v80 offset:10432
	s_waitcnt lgkmcnt(3)
	v_mfma_f32_16x16x32_bf16 v[68:71], v[72:75], v[32:35], v[68:71]
	s_waitcnt lgkmcnt(2)
	v_mfma_f32_16x16x32_bf16 v[68:71], v[76:79], v[36:39], v[68:71]
	s_waitcnt vmcnt(3)
	v_mov_b64_e32 v[82:83], v[54:55]
	v_mov_b64_e32 v[80:81], v[52:53]
	s_waitcnt lgkmcnt(1)
	v_mfma_f32_16x16x32_bf16 v[68:71], v[184:187], v[40:43], v[68:71]
	s_waitcnt lgkmcnt(0)
	v_mfma_f32_16x16x32_bf16 v[68:71], v[188:191], v[44:47], v[68:71]
	s_waitcnt vmcnt(2)
	v_mov_b64_e32 v[78:79], v[58:59]
	v_mov_b64_e32 v[76:77], v[56:57]
	s_nop 4
	v_pk_mul_f32 v[232:233], v[68:69], v[224:225]
	v_pk_mul_f32 v[234:235], v[70:71], v[224:225]
	v_pk_fma_f32 v[232:233], v[68:69], v[232:233], v[226:227]
	v_pk_fma_f32 v[234:235], v[70:71], v[234:235], v[226:227]
	v_pk_mul_f32 v[232:233], v[68:69], v[232:233]
	v_pk_mul_f32 v[234:235], v[70:71], v[234:235]
	v_pk_mul_f32 v[232:233], v[232:233], v[228:229]
	v_pk_mul_f32 v[234:235], v[234:235], v[228:229]
	v_exp_f32_e32 v232, v232
	v_exp_f32_e32 v233, v233
	v_exp_f32_e32 v234, v234
	v_exp_f32_e32 v235, v235
	v_pk_add_f32 v[232:233], v[232:233], v[230:231]
	v_pk_add_f32 v[234:235], v[234:235], v[230:231]
	v_rcp_f32_e32 v232, v232
	v_rcp_f32_e32 v233, v233
	v_rcp_f32_e32 v234, v234
	v_rcp_f32_e32 v235, v235
	v_pk_mul_f32 v[232:233], v[68:69], v[232:233]
	v_pk_mul_f32 v[234:235], v[70:71], v[234:235]
	v_cvt_pk_bf16_f32 v236, v232, v232
	v_cvt_pk_bf16_f32 v237, v233, v233
	v_cvt_pk_bf16_f32 v238, v234, v234
	v_cvt_pk_bf16_f32 v239, v235, v235
	ds_write_b16 v160, v236 offset:16128
	ds_write_b16 v160, v237 offset:16160
	ds_write_b16 v160, v238 offset:16192
	ds_write_b16 v164, v239 offset:14592
	s_waitcnt vmcnt(1)
	v_mov_b64_e32 v[74:75], v[62:63]
	v_mov_b64_e32 v[72:73], v[60:61]
	s_waitcnt lgkmcnt(0)
	s_waitcnt vmcnt(0)
	v_mov_b64_e32 v[70:71], v[66:67]
	v_mov_b64_e32 v[68:69], v[64:65]

.LBB0_875:
	s_cmp_eq_u32 s30, 0
	s_cselect_b64 s[34:35], -1, 0
	s_and_b64 vcc, exec, s[34:35]
	s_cbranch_vccz .LBB0_877


	s_andn2_b64 vcc, exec, s[34:35]
	s_mov_b64 s[34:35], -1
	s_cbranch_vccnz .LBB0_874
	s_branch .LBB0_878
